# indexer: last chunk of each wave processed without issuing further K loads (no reads past the end, ~11% less indexer traffic)
# speedup vs baseline: 1.0192x; 1.0192x over previous
; #define TILE_LOAD(SLOT, CC, TT) do { const bf16_t* kp = P.KI + (rowb + 64 * (CC) + 16 * (TT) + r16) * 64 + 8 * g; Bk[SLOT][0] = *(const bf16x8*)kp; Bk[SLOT][1] = *(const bf16x8*)(kp + 32); } while (0)
; #define TILE_MATH(SLOT, TT) do { _Pragma("unroll") for (int q = 0; q < 4; ++q) { f32x4 a = {0.f, 0.f, 0.f, 0.f}; \
;             a = mfma16(Aq[q][0], Bk[SLOT][0], a); a = mfma16(Aq[q][1], Bk[SLOT][1], a); \
;             pv[q][TT] = wq[q][0] * fmaxf(a[0], 0.f) + wq[q][1] * fmaxf(a[1], 0.f) + wq[q][2] * fmaxf(a[2], 0.f) + wq[q][3] * fmaxf(a[3], 0.f); } } while (0)
; __device__ __forceinline__ void attn_item(const Ptrs& P, unsigned char* lds, int b, int tq0, int tid) {
;     ...
;         for (int q = 0; q < 4; ++q) { const bf16_t* qp = P.QI + (rowb + tq0 + q) * 1024 + r16 * 64 + 8 * g; Aq[q][0] = *(const bf16x8*)qp; Aq[q][1] = *(const bf16x8*)(qp + 32);
;             wq[q] = *(const f32x4*)(P.WI + (rowb + tq0 + q) * 16 + 4 * g); }
;         unsigned* KB = (unsigned*)lds;
;         const int nch = (tmax >> 6) + 1;
;         const int ni = (w < nch) ? ((nch - w + 7) >> 3) : 0;
;         bf16x8 Bk[4][2];
;     ...
;         if (ni > 0) { TILE_LOAD(0, w, 0); TILE_LOAD(1, w, 1); }
; #pragma unroll 1
;         for (int it = 0; it < ni; ++it) {
;             const int c = 8 * it + w; const bool more = it + 1 < ni;
;             float pv[4][4], sv[4];
;             TILE_LOAD(2, c, 2); TILE_MATH(0, 0);
;             TILE_LOAD(3, c, 3); TILE_MATH(1, 1);
;             if (more) TILE_LOAD(0, c + 8, 0);
;             TILE_MATH(2, 2);
;             if (more) TILE_LOAD(1, c + 8, 1);
;             TILE_MATH(3, 3);
.Lq_have_item:
	s_movk_i32 s12, 0x800
	s_waitcnt lgkmcnt(0)
	v_cmp_gt_i32_e32 vcc, s12, v0
	s_mov_b64 s[12:13], -1
	s_and_saveexec_b64 s[70:71], vcc
	s_cbranch_execz .LBB0_465
	v_lshlrev_b32_e32 v64, 2, v0
	v_sub_u32_e32 v124, 0x1ffc, v64
	v_readfirstlane_b32 s63, v188
	s_movk_i32 s12, 0xfc
	s_lshr_b32 s62, s63, 6
	v_cmp_lt_u32_e32 vcc, s12, v124
	s_and_saveexec_b64 s[12:13], vcc
	s_xor_b64 s[60:61], exec, s[12:13]
	s_cbranch_execz .LBB0_913
	v_sub_u32_e32 v126, 0x1fff, v64
	v_lshrrev_b32_e32 v125, 6, v126
	v_subrev_u32_e32 v0, s62, v125
	v_add_u32_e32 v65, 8, v0
	v_cmp_le_u32_e32 vcc, s62, v125
	v_cmp_lt_u32_e64 s[12:13], 7, v65
	s_and_b64 s[14:15], vcc, s[12:13]
	s_and_saveexec_b64 s[12:13], s[14:15]
	s_cbranch_execz .LBB0_479
	s_and_b32 s14, s63, 0xffffffc0
	v_add_u32_e32 v164, s81, v124
	s_ashr_i32 s15, s14, 31
	v_or_b32_e32 v40, 1, v164
	v_mov_b32_e32 v41, v165
	v_or_b32_e32 v32, 2, v164
	v_mov_b32_e32 v33, v165
	v_or_b32_e32 v34, 3, v164
	v_mov_b32_e32 v35, v165
	v_lshl_add_u64 v[48:49], s[14:15], 0, v[182:183]
	v_lshlrev_b64 v[0:1], 11, v[164:165]
	v_lshlrev_b64 v[8:9], 11, v[40:41]
	v_lshlrev_b64 v[16:17], 11, v[32:33]
	v_lshlrev_b64 v[24:25], 11, v[34:35]
	v_lshlrev_b64 v[34:35], 6, v[34:35]
	v_lshlrev_b64 v[32:33], 6, v[32:33]
	v_lshlrev_b64 v[40:41], 6, v[40:41]
	v_lshlrev_b64 v[42:43], 6, v[164:165]
	v_lshlrev_b64 v[48:49], 7, v[48:49]
	v_lshl_add_u64 v[4:5], v[168:169], 0, v[0:1]
	v_lshl_add_u64 v[12:13], v[168:169], 0, v[8:9]
	v_lshl_add_u64 v[20:21], v[168:169], 0, v[16:17]
	v_lshl_add_u64 v[28:29], v[168:169], 0, v[24:25]
	v_lshl_add_u64 v[34:35], v[170:171], 0, v[34:35]
	v_lshl_add_u64 v[36:37], v[170:171], 0, v[32:33]
	v_lshl_add_u64 v[40:41], v[170:171], 0, v[40:41]
	v_lshl_add_u64 v[44:45], v[170:171], 0, v[42:43]
	v_lshl_add_u64 v[60:61], v[172:173], 0, v[48:49]
	global_load_dwordx4 v[0:3], v[4:5], off
	s_nop 0
	global_load_dwordx4 v[4:7], v[4:5], off offset:64
	s_nop 0
	global_load_dwordx4 v[8:11], v[12:13], off
	s_nop 0
	global_load_dwordx4 v[12:15], v[12:13], off offset:64
	s_nop 0
	global_load_dwordx4 v[16:19], v[20:21], off
	s_nop 0
	global_load_dwordx4 v[20:23], v[20:21], off offset:64
	s_nop 0
	global_load_dwordx4 v[24:27], v[28:29], off
	s_nop 0
	global_load_dwordx4 v[28:31], v[28:29], off offset:64
	s_nop 0
	global_load_dwordx4 v[32:35], v[34:35], off
	s_nop 0
	global_load_dwordx4 v[36:39], v[36:37], off
	s_nop 0
	global_load_dwordx4 v[40:43], v[40:41], off
	s_nop 0
	global_load_dwordx4 v[44:47], v[44:45], off
	s_nop 0
	v_lshrrev_b32_e32 v127, 3, v65
	v_sub_u32_e32 v128, 0x1ffd, v64
	v_sub_u32_e32 v129, 0x1ffe, v64
	v_mov_b64_e32 v[150:151], v[60:61]
	s_mov_b64 s[18:19], 0x1000
	v_lshl_add_u64 v[152:153], v[60:61], 0, s[18:19]
	global_load_dwordx4 v[48:51], v[150:151], off
	global_load_dwordx4 v[52:55], v[150:151], off offset:1024
	global_load_dwordx4 v[56:59], v[150:151], off offset:2048
	global_load_dwordx4 v[60:63], v[150:151], off offset:3072
	global_load_dwordx4 v[64:67], v[152:153], off
	global_load_dwordx4 v[68:71], v[152:153], off offset:1024
	global_load_dwordx4 v[72:75], v[152:153], off offset:2048
	global_load_dwordx4 v[76:79], v[152:153], off offset:3072
	s_mov_b64 s[18:19], 0x10000
	v_lshl_add_u64 v[150:151], v[150:151], 0, s[18:19]
	v_lshl_add_u64 v[152:153], v[152:153], 0, s[18:19]
	s_mov_b32 s20, 0
	v_lshl_add_u32 v130, s62, 8, v203
	v_add_u32_e32 v155, 0x10000, v130
	v_add_u32_e32 v154, s14, v179
	s_nop 0
	v_readfirstlane_b32 s14, v127
	s_sub_i32 s15, s14, 1
	s_cmp_lt_u32 s20, s15
	s_cbranch_scc0 .Lidx_last
.Lidx_loop:
	s_waitcnt vmcnt(6)
	v_mfma_f32_16x16x32_bf16 v[80:83], v[0:3], v[48:51], 0
	v_mfma_f32_16x16x32_bf16 v[84:87], v[8:11], v[48:51], 0
	v_mfma_f32_16x16x32_bf16 v[88:91], v[16:19], v[48:51], 0
	v_mfma_f32_16x16x32_bf16 v[92:95], v[24:27], v[48:51], 0
	v_mfma_f32_16x16x32_bf16 v[80:83], v[4:7], v[52:55], v[80:83]
	v_mfma_f32_16x16x32_bf16 v[84:87], v[12:15], v[52:55], v[84:87]
	v_mfma_f32_16x16x32_bf16 v[88:91], v[20:23], v[52:55], v[88:91]
	v_mfma_f32_16x16x32_bf16 v[92:95], v[28:31], v[52:55], v[92:95]
	global_load_dwordx4 v[48:51], v[150:151], off
	global_load_dwordx4 v[52:55], v[150:151], off offset:1024
	s_waitcnt vmcnt(6)
	v_mfma_f32_16x16x32_bf16 v[96:99], v[0:3], v[56:59], 0
	v_mfma_f32_16x16x32_bf16 v[100:103], v[8:11], v[56:59], 0
	v_mfma_f32_16x16x32_bf16 v[104:107], v[16:19], v[56:59], 0
	v_mfma_f32_16x16x32_bf16 v[108:111], v[24:27], v[56:59], 0
	v_mfma_f32_16x16x32_bf16 v[96:99], v[4:7], v[60:63], v[96:99]
	v_mfma_f32_16x16x32_bf16 v[100:103], v[12:15], v[60:63], v[100:103]
	v_mfma_f32_16x16x32_bf16 v[104:107], v[20:23], v[60:63], v[104:107]
	v_mfma_f32_16x16x32_bf16 v[108:111], v[28:31], v[60:63], v[108:111]
	global_load_dwordx4 v[56:59], v[150:151], off offset:2048
	global_load_dwordx4 v[60:63], v[150:151], off offset:3072
	v_max_f32_e32 v80, 0, v80
	v_max_f32_e32 v84, 0, v84
	v_max_f32_e32 v88, 0, v88
	v_max_f32_e32 v92, 0, v92
	v_max_f32_e32 v81, 0, v81
	v_max_f32_e32 v85, 0, v85
	v_max_f32_e32 v89, 0, v89
	v_max_f32_e32 v93, 0, v93
	v_max_f32_e32 v82, 0, v82
	v_max_f32_e32 v86, 0, v86
	v_max_f32_e32 v90, 0, v90
	v_max_f32_e32 v94, 0, v94
	v_max_f32_e32 v83, 0, v83
	v_max_f32_e32 v87, 0, v87
	v_max_f32_e32 v91, 0, v91
	v_max_f32_e32 v95, 0, v95
	v_mul_f32_e32 v132, v44, v80
	v_mul_f32_e32 v136, v40, v84
	v_mul_f32_e32 v140, v36, v88
	v_mul_f32_e32 v144, v32, v92
	v_fmac_f32_e32 v132, v45, v81
	v_fmac_f32_e32 v136, v41, v85
	v_fmac_f32_e32 v140, v37, v89
	v_fmac_f32_e32 v144, v33, v93
	v_fmac_f32_e32 v132, v46, v82
	v_fmac_f32_e32 v136, v42, v86
	v_fmac_f32_e32 v140, v38, v90
	v_fmac_f32_e32 v144, v34, v94
	v_fmac_f32_e32 v132, v47, v83
	v_fmac_f32_e32 v136, v43, v87
	v_fmac_f32_e32 v140, v39, v91
	v_fmac_f32_e32 v144, v35, v95
	s_waitcnt vmcnt(6)
; __device__ __forceinline__ unsigned f2key(float f) { const unsigned u = __builtin_bit_cast(unsigned, f); return (u & 0x80000000u) ? ~u : (u | 0x80000000u); }
; #define TILE_LOAD(SLOT, CC, TT) do { const bf16_t* kp = P.KI + (rowb + 64 * (CC) + 16 * (TT) + r16) * 64 + 8 * g; Bk[SLOT][0] = *(const bf16x8*)kp; Bk[SLOT][1] = *(const bf16x8*)(kp + 32); } while (0)
; #define TILE_MATH(SLOT, TT) do { _Pragma("unroll") for (int q = 0; q < 4; ++q) { f32x4 a = {0.f, 0.f, 0.f, 0.f}; \
;             a = mfma16(Aq[q][0], Bk[SLOT][0], a); a = mfma16(Aq[q][1], Bk[SLOT][1], a); \
;             pv[q][TT] = wq[q][0] * fmaxf(a[0], 0.f) + wq[q][1] * fmaxf(a[1], 0.f) + wq[q][2] * fmaxf(a[2], 0.f) + wq[q][3] * fmaxf(a[3], 0.f); } } while (0)
; __device__ __forceinline__ void attn_item(const Ptrs& P, unsigned char* lds, int b, int tq0, int tid) {
;     ...
;             TILE_LOAD(2, c, 2); TILE_MATH(0, 0);
;             TILE_LOAD(3, c, 3); TILE_MATH(1, 1);
;             if (more) TILE_LOAD(0, c + 8, 0);
;             TILE_MATH(2, 2);
;             if (more) TILE_LOAD(1, c + 8, 1);
;             TILE_MATH(3, 3);
; #pragma unroll
;             for (int q = 0; q < 4; ++q) { float a0 = pv[q][0], b0 = pv[q][2], a1 = pv[q][1], b1 = pv[q][3];
;                 asm("s_nop 1\n\tv_permlane32_swap_b32 %0, %1" : "+v"(a0), "+v"(b0));
;                 asm("s_nop 1\n\tv_permlane32_swap_b32 %0, %1" : "+v"(a1), "+v"(b1));
;                 float x = a0 + b0, y = a1 + b1;
;                 asm("s_nop 1\n\tv_permlane16_swap_b32 %0, %1" : "+v"(x), "+v"(y));
;                 sv[q] = x + y; }
;             const int s = 64 * c + lane;
; #pragma unroll
;             for (int q = 0; q < 4; ++q) KB[q * 8192 + s] = (s <= tq0 + q) ? f2key(sv[q]) : 0u;
	v_mfma_f32_16x16x32_bf16 v[80:83], v[0:3], v[64:67], 0
	v_mfma_f32_16x16x32_bf16 v[84:87], v[8:11], v[64:67], 0
	v_mfma_f32_16x16x32_bf16 v[88:91], v[16:19], v[64:67], 0
	v_mfma_f32_16x16x32_bf16 v[92:95], v[24:27], v[64:67], 0
	v_mfma_f32_16x16x32_bf16 v[80:83], v[4:7], v[68:71], v[80:83]
	v_mfma_f32_16x16x32_bf16 v[84:87], v[12:15], v[68:71], v[84:87]
	v_mfma_f32_16x16x32_bf16 v[88:91], v[20:23], v[68:71], v[88:91]
	v_mfma_f32_16x16x32_bf16 v[92:95], v[28:31], v[68:71], v[92:95]
	global_load_dwordx4 v[64:67], v[152:153], off
	global_load_dwordx4 v[68:71], v[152:153], off offset:1024
	v_max_f32_e32 v96, 0, v96
	v_max_f32_e32 v100, 0, v100
	v_max_f32_e32 v104, 0, v104
	v_max_f32_e32 v108, 0, v108
	v_max_f32_e32 v97, 0, v97
	v_max_f32_e32 v101, 0, v101
	v_max_f32_e32 v105, 0, v105
	v_max_f32_e32 v109, 0, v109
	v_max_f32_e32 v98, 0, v98
	v_max_f32_e32 v102, 0, v102
	v_max_f32_e32 v106, 0, v106
	v_max_f32_e32 v110, 0, v110
	v_max_f32_e32 v99, 0, v99
	v_max_f32_e32 v103, 0, v103
	v_max_f32_e32 v107, 0, v107
	v_max_f32_e32 v111, 0, v111
	v_mul_f32_e32 v133, v44, v96
	v_mul_f32_e32 v137, v40, v100
	v_mul_f32_e32 v141, v36, v104
	v_mul_f32_e32 v145, v32, v108
	v_fmac_f32_e32 v133, v45, v97
	v_fmac_f32_e32 v137, v41, v101
	v_fmac_f32_e32 v141, v37, v105
	v_fmac_f32_e32 v145, v33, v109
	v_fmac_f32_e32 v133, v46, v98
	v_fmac_f32_e32 v137, v42, v102
	v_fmac_f32_e32 v141, v38, v106
	v_fmac_f32_e32 v145, v34, v110
	v_fmac_f32_e32 v133, v47, v99
	v_fmac_f32_e32 v137, v43, v103
	v_fmac_f32_e32 v141, v39, v107
	v_fmac_f32_e32 v145, v35, v111
	s_waitcnt vmcnt(6)
	v_mfma_f32_16x16x32_bf16 v[96:99], v[0:3], v[72:75], 0
	v_mfma_f32_16x16x32_bf16 v[100:103], v[8:11], v[72:75], 0
	v_mfma_f32_16x16x32_bf16 v[104:107], v[16:19], v[72:75], 0
	v_mfma_f32_16x16x32_bf16 v[108:111], v[24:27], v[72:75], 0
	v_mfma_f32_16x16x32_bf16 v[96:99], v[4:7], v[76:79], v[96:99]
	v_mfma_f32_16x16x32_bf16 v[100:103], v[12:15], v[76:79], v[100:103]
	v_mfma_f32_16x16x32_bf16 v[104:107], v[20:23], v[76:79], v[104:107]
	v_mfma_f32_16x16x32_bf16 v[108:111], v[28:31], v[76:79], v[108:111]
	global_load_dwordx4 v[72:75], v[152:153], off offset:2048
	global_load_dwordx4 v[76:79], v[152:153], off offset:3072
	v_lshl_add_u64 v[150:151], v[150:151], 0, s[18:19]
	v_lshl_add_u64 v[152:153], v[152:153], 0, s[18:19]
	v_max_f32_e32 v80, 0, v80
	v_max_f32_e32 v84, 0, v84
	v_max_f32_e32 v88, 0, v88
	v_max_f32_e32 v92, 0, v92
	v_max_f32_e32 v81, 0, v81
	v_max_f32_e32 v85, 0, v85
	v_max_f32_e32 v89, 0, v89
	v_max_f32_e32 v93, 0, v93
	v_max_f32_e32 v82, 0, v82
	v_max_f32_e32 v86, 0, v86
	v_max_f32_e32 v90, 0, v90
	v_max_f32_e32 v94, 0, v94
	v_max_f32_e32 v83, 0, v83
	v_max_f32_e32 v87, 0, v87
	v_max_f32_e32 v91, 0, v91
	v_max_f32_e32 v95, 0, v95
	v_mul_f32_e32 v134, v44, v80
	v_mul_f32_e32 v138, v40, v84
	v_mul_f32_e32 v142, v36, v88
	v_mul_f32_e32 v146, v32, v92
	v_fmac_f32_e32 v134, v45, v81
	v_fmac_f32_e32 v138, v41, v85
	v_fmac_f32_e32 v142, v37, v89
	v_fmac_f32_e32 v146, v33, v93
	v_fmac_f32_e32 v134, v46, v82
	v_fmac_f32_e32 v138, v42, v86
	v_fmac_f32_e32 v142, v38, v90
	v_fmac_f32_e32 v146, v34, v94
	v_fmac_f32_e32 v134, v47, v83
	v_fmac_f32_e32 v138, v43, v87
	v_fmac_f32_e32 v142, v39, v91
	v_fmac_f32_e32 v146, v35, v95
	v_max_f32_e32 v96, 0, v96
	v_max_f32_e32 v100, 0, v100
	v_max_f32_e32 v104, 0, v104
	v_max_f32_e32 v108, 0, v108
	v_max_f32_e32 v97, 0, v97
	v_max_f32_e32 v101, 0, v101
	v_max_f32_e32 v105, 0, v105
	v_max_f32_e32 v109, 0, v109
	v_max_f32_e32 v98, 0, v98
	v_max_f32_e32 v102, 0, v102
	v_max_f32_e32 v106, 0, v106
	v_max_f32_e32 v110, 0, v110
	v_max_f32_e32 v99, 0, v99
	v_max_f32_e32 v103, 0, v103
	v_max_f32_e32 v107, 0, v107
	v_max_f32_e32 v111, 0, v111
	v_mul_f32_e32 v135, v44, v96
	v_mul_f32_e32 v139, v40, v100
	v_mul_f32_e32 v143, v36, v104
	v_mul_f32_e32 v147, v32, v108
	v_fmac_f32_e32 v135, v45, v97
	v_fmac_f32_e32 v139, v41, v101
	v_fmac_f32_e32 v143, v37, v105
	v_fmac_f32_e32 v147, v33, v109
	v_fmac_f32_e32 v135, v46, v98
	v_fmac_f32_e32 v139, v42, v102
	v_fmac_f32_e32 v143, v38, v106
	v_fmac_f32_e32 v147, v34, v110
	v_fmac_f32_e32 v135, v47, v99
	v_fmac_f32_e32 v139, v43, v103
	v_fmac_f32_e32 v143, v39, v107
	v_fmac_f32_e32 v147, v35, v111
	s_nop 1
	v_permlane32_swap_b32_e32 v132, v134
	v_permlane32_swap_b32_e32 v133, v135
	v_permlane32_swap_b32_e32 v136, v138
	v_permlane32_swap_b32_e32 v137, v139
	v_permlane32_swap_b32_e32 v140, v142
	v_permlane32_swap_b32_e32 v141, v143
	v_permlane32_swap_b32_e32 v144, v146
	v_permlane32_swap_b32_e32 v145, v147
	v_add_f32_e32 v112, v132, v134
	v_add_f32_e32 v113, v133, v135
	v_add_f32_e32 v114, v136, v138
	v_add_f32_e32 v115, v137, v139
	v_add_f32_e32 v116, v140, v142
	v_add_f32_e32 v117, v141, v143
	v_add_f32_e32 v118, v144, v146
	v_add_f32_e32 v119, v145, v147
	s_nop 1
	v_permlane16_swap_b32_e32 v112, v113
	v_permlane16_swap_b32_e32 v114, v115
	v_permlane16_swap_b32_e32 v116, v117
	v_permlane16_swap_b32_e32 v118, v119
	v_add_u32_e32 v156, 0x800, v130
	v_add_u32_e32 v157, 0x800, v155
	v_add_f32_e32 v120, v112, v113
	v_add_f32_e32 v121, v114, v115
	v_add_f32_e32 v122, v116, v117
	v_add_f32_e32 v123, v118, v119
	v_ashrrev_i32_e32 v112, 31, v120
	v_ashrrev_i32_e32 v113, 31, v121
	v_ashrrev_i32_e32 v114, 31, v122
	v_ashrrev_i32_e32 v115, 31, v123
	v_cmp_le_u32_e32 vcc, v154, v124
	v_cmp_le_u32_e64 s[16:17], v154, v128
	v_cmp_le_u32_e64 s[44:45], v154, v129
	v_cmp_le_u32_e64 s[78:79], v154, v126
	v_or_b32_e32 v112, 0x80000000, v112
	v_or_b32_e32 v113, 0x80000000, v113
	v_or_b32_e32 v114, 0x80000000, v114
	v_or_b32_e32 v115, 0x80000000, v115
	v_xor_b32_e32 v120, v120, v112
	v_xor_b32_e32 v121, v121, v113
	v_xor_b32_e32 v122, v122, v114
	v_xor_b32_e32 v123, v123, v115
	v_cndmask_b32_e32 v120, 0, v120, vcc
	v_cndmask_b32_e64 v121, 0, v121, s[16:17]
	v_cndmask_b32_e64 v122, 0, v122, s[44:45]
	v_cndmask_b32_e64 v123, 0, v123, s[78:79]
	ds_write2st64_b32 v130, v120, v121 offset1:128
	ds_write2st64_b32 v155, v122, v123 offset1:128
	v_mov_b32_e32 v130, v156
	v_mov_b32_e32 v155, v157
	v_add_u32_e32 v154, 0x200, v154
	s_add_i32 s20, s20, 1
	s_cmp_lt_u32 s20, s15
	s_cbranch_scc1 .Lidx_loop
; #define TILE_LOAD(SLOT, CC, TT) do { const bf16_t* kp = P.KI + (rowb + 64 * (CC) + 16 * (TT) + r16) * 64 + 8 * g; Bk[SLOT][0] = *(const bf16x8*)kp; Bk[SLOT][1] = *(const bf16x8*)(kp + 32); } while (0)
; #define TILE_MATH(SLOT, TT) do { _Pragma("unroll") for (int q = 0; q < 4; ++q) { f32x4 a = {0.f, 0.f, 0.f, 0.f}; \
;             a = mfma16(Aq[q][0], Bk[SLOT][0], a); a = mfma16(Aq[q][1], Bk[SLOT][1], a); \
;             pv[q][TT] = wq[q][0] * fmaxf(a[0], 0.f) + wq[q][1] * fmaxf(a[1], 0.f) + wq[q][2] * fmaxf(a[2], 0.f) + wq[q][3] * fmaxf(a[3], 0.f); } } while (0)
; __device__ __forceinline__ void attn_item(const Ptrs& P, unsigned char* lds, int b, int tq0, int tid) {
;     ...
;         if (ni > 0) { TILE_LOAD(0, w, 0); TILE_LOAD(1, w, 1); }
; #pragma unroll 1
;         for (int it = 0; it < ni; ++it) {
;             const int c = 8 * it + w; const bool more = it + 1 < ni;
;             float pv[4][4], sv[4];
;             TILE_LOAD(2, c, 2); TILE_MATH(0, 0);
;             TILE_LOAD(3, c, 3); TILE_MATH(1, 1);
;             if (more) TILE_LOAD(0, c + 8, 0);
;             TILE_MATH(2, 2);
;             if (more) TILE_LOAD(1, c + 8, 1);
;             TILE_MATH(3, 3);
.Lidx_last:
	s_waitcnt vmcnt(6)
	v_mfma_f32_16x16x32_bf16 v[80:83], v[0:3], v[48:51], 0
	v_mfma_f32_16x16x32_bf16 v[84:87], v[8:11], v[48:51], 0
	v_mfma_f32_16x16x32_bf16 v[88:91], v[16:19], v[48:51], 0
	v_mfma_f32_16x16x32_bf16 v[92:95], v[24:27], v[48:51], 0
	v_mfma_f32_16x16x32_bf16 v[80:83], v[4:7], v[52:55], v[80:83]
	v_mfma_f32_16x16x32_bf16 v[84:87], v[12:15], v[52:55], v[84:87]
	v_mfma_f32_16x16x32_bf16 v[88:91], v[20:23], v[52:55], v[88:91]
	v_mfma_f32_16x16x32_bf16 v[92:95], v[28:31], v[52:55], v[92:95]
	s_waitcnt vmcnt(4)
	v_mfma_f32_16x16x32_bf16 v[96:99], v[0:3], v[56:59], 0
	v_mfma_f32_16x16x32_bf16 v[100:103], v[8:11], v[56:59], 0
	v_mfma_f32_16x16x32_bf16 v[104:107], v[16:19], v[56:59], 0
	v_mfma_f32_16x16x32_bf16 v[108:111], v[24:27], v[56:59], 0
	v_mfma_f32_16x16x32_bf16 v[96:99], v[4:7], v[60:63], v[96:99]
	v_mfma_f32_16x16x32_bf16 v[100:103], v[12:15], v[60:63], v[100:103]
	v_mfma_f32_16x16x32_bf16 v[104:107], v[20:23], v[60:63], v[104:107]
	v_mfma_f32_16x16x32_bf16 v[108:111], v[28:31], v[60:63], v[108:111]
	v_max_f32_e32 v80, 0, v80
	v_max_f32_e32 v84, 0, v84
	v_max_f32_e32 v88, 0, v88
	v_max_f32_e32 v92, 0, v92
	v_max_f32_e32 v81, 0, v81
	v_max_f32_e32 v85, 0, v85
	v_max_f32_e32 v89, 0, v89
	v_max_f32_e32 v93, 0, v93
	v_max_f32_e32 v82, 0, v82
	v_max_f32_e32 v86, 0, v86
	v_max_f32_e32 v90, 0, v90
	v_max_f32_e32 v94, 0, v94
	v_max_f32_e32 v83, 0, v83
	v_max_f32_e32 v87, 0, v87
	v_max_f32_e32 v91, 0, v91
	v_max_f32_e32 v95, 0, v95
	v_mul_f32_e32 v132, v44, v80
	v_mul_f32_e32 v136, v40, v84
	v_mul_f32_e32 v140, v36, v88
	v_mul_f32_e32 v144, v32, v92
	v_fmac_f32_e32 v132, v45, v81
	v_fmac_f32_e32 v136, v41, v85
	v_fmac_f32_e32 v140, v37, v89
	v_fmac_f32_e32 v144, v33, v93
	v_fmac_f32_e32 v132, v46, v82
	v_fmac_f32_e32 v136, v42, v86
	v_fmac_f32_e32 v140, v38, v90
	v_fmac_f32_e32 v144, v34, v94
	v_fmac_f32_e32 v132, v47, v83
	v_fmac_f32_e32 v136, v43, v87
	v_fmac_f32_e32 v140, v39, v91
	v_fmac_f32_e32 v144, v35, v95
	s_waitcnt vmcnt(2)
	v_mfma_f32_16x16x32_bf16 v[80:83], v[0:3], v[64:67], 0
	v_mfma_f32_16x16x32_bf16 v[84:87], v[8:11], v[64:67], 0
	v_mfma_f32_16x16x32_bf16 v[88:91], v[16:19], v[64:67], 0
	v_mfma_f32_16x16x32_bf16 v[92:95], v[24:27], v[64:67], 0
	v_mfma_f32_16x16x32_bf16 v[80:83], v[4:7], v[68:71], v[80:83]
	v_mfma_f32_16x16x32_bf16 v[84:87], v[12:15], v[68:71], v[84:87]
	v_mfma_f32_16x16x32_bf16 v[88:91], v[20:23], v[68:71], v[88:91]
	v_mfma_f32_16x16x32_bf16 v[92:95], v[28:31], v[68:71], v[92:95]
	v_max_f32_e32 v96, 0, v96
	v_max_f32_e32 v100, 0, v100
	v_max_f32_e32 v104, 0, v104
	v_max_f32_e32 v108, 0, v108
	v_max_f32_e32 v97, 0, v97
	v_max_f32_e32 v101, 0, v101
	v_max_f32_e32 v105, 0, v105
	v_max_f32_e32 v109, 0, v109
	v_max_f32_e32 v98, 0, v98
	v_max_f32_e32 v102, 0, v102
	v_max_f32_e32 v106, 0, v106
	v_max_f32_e32 v110, 0, v110
	v_max_f32_e32 v99, 0, v99
	v_max_f32_e32 v103, 0, v103
	v_max_f32_e32 v107, 0, v107
	v_max_f32_e32 v111, 0, v111
	v_mul_f32_e32 v133, v44, v96
	v_mul_f32_e32 v137, v40, v100
	v_mul_f32_e32 v141, v36, v104
	v_mul_f32_e32 v145, v32, v108
	v_fmac_f32_e32 v133, v45, v97
	v_fmac_f32_e32 v137, v41, v101
	v_fmac_f32_e32 v141, v37, v105
	v_fmac_f32_e32 v145, v33, v109
	v_fmac_f32_e32 v133, v46, v98
	v_fmac_f32_e32 v137, v42, v102
	v_fmac_f32_e32 v141, v38, v106
	v_fmac_f32_e32 v145, v34, v110
	v_fmac_f32_e32 v133, v47, v99
	v_fmac_f32_e32 v137, v43, v103
	v_fmac_f32_e32 v141, v39, v107
	v_fmac_f32_e32 v145, v35, v111
	s_waitcnt vmcnt(0)
; __device__ __forceinline__ unsigned f2key(float f) { const unsigned u = __builtin_bit_cast(unsigned, f); return (u & 0x80000000u) ? ~u : (u | 0x80000000u); }
; #define TILE_LOAD(SLOT, CC, TT) do { const bf16_t* kp = P.KI + (rowb + 64 * (CC) + 16 * (TT) + r16) * 64 + 8 * g; Bk[SLOT][0] = *(const bf16x8*)kp; Bk[SLOT][1] = *(const bf16x8*)(kp + 32); } while (0)
; #define TILE_MATH(SLOT, TT) do { _Pragma("unroll") for (int q = 0; q < 4; ++q) { f32x4 a = {0.f, 0.f, 0.f, 0.f}; \
;             a = mfma16(Aq[q][0], Bk[SLOT][0], a); a = mfma16(Aq[q][1], Bk[SLOT][1], a); \
;             pv[q][TT] = wq[q][0] * fmaxf(a[0], 0.f) + wq[q][1] * fmaxf(a[1], 0.f) + wq[q][2] * fmaxf(a[2], 0.f) + wq[q][3] * fmaxf(a[3], 0.f); } } while (0)
; __device__ __forceinline__ void attn_item(const Ptrs& P, unsigned char* lds, int b, int tq0, int tid) {
;     ...
;             TILE_MATH(2, 2);
;             if (more) TILE_LOAD(1, c + 8, 1);
;             TILE_MATH(3, 3);
; #pragma unroll
;             for (int q = 0; q < 4; ++q) { float a0 = pv[q][0], b0 = pv[q][2], a1 = pv[q][1], b1 = pv[q][3];
;                 asm("s_nop 1\n\tv_permlane32_swap_b32 %0, %1" : "+v"(a0), "+v"(b0));
;                 asm("s_nop 1\n\tv_permlane32_swap_b32 %0, %1" : "+v"(a1), "+v"(b1));
;                 float x = a0 + b0, y = a1 + b1;
;                 asm("s_nop 1\n\tv_permlane16_swap_b32 %0, %1" : "+v"(x), "+v"(y));
;                 sv[q] = x + y; }
;             const int s = 64 * c + lane;
; #pragma unroll
;             for (int q = 0; q < 4; ++q) KB[q * 8192 + s] = (s <= tq0 + q) ? f2key(sv[q]) : 0u;
	v_mfma_f32_16x16x32_bf16 v[96:99], v[0:3], v[72:75], 0
	v_mfma_f32_16x16x32_bf16 v[100:103], v[8:11], v[72:75], 0
	v_mfma_f32_16x16x32_bf16 v[104:107], v[16:19], v[72:75], 0
	v_mfma_f32_16x16x32_bf16 v[108:111], v[24:27], v[72:75], 0
	v_mfma_f32_16x16x32_bf16 v[96:99], v[4:7], v[76:79], v[96:99]
	v_mfma_f32_16x16x32_bf16 v[100:103], v[12:15], v[76:79], v[100:103]
	v_mfma_f32_16x16x32_bf16 v[104:107], v[20:23], v[76:79], v[104:107]
	v_mfma_f32_16x16x32_bf16 v[108:111], v[28:31], v[76:79], v[108:111]
	v_max_f32_e32 v80, 0, v80
	v_max_f32_e32 v84, 0, v84
	v_max_f32_e32 v88, 0, v88
	v_max_f32_e32 v92, 0, v92
	v_max_f32_e32 v81, 0, v81
	v_max_f32_e32 v85, 0, v85
	v_max_f32_e32 v89, 0, v89
	v_max_f32_e32 v93, 0, v93
	v_max_f32_e32 v82, 0, v82
	v_max_f32_e32 v86, 0, v86
	v_max_f32_e32 v90, 0, v90
	v_max_f32_e32 v94, 0, v94
	v_max_f32_e32 v83, 0, v83
	v_max_f32_e32 v87, 0, v87
	v_max_f32_e32 v91, 0, v91
	v_max_f32_e32 v95, 0, v95
	v_mul_f32_e32 v134, v44, v80
	v_mul_f32_e32 v138, v40, v84
	v_mul_f32_e32 v142, v36, v88
	v_mul_f32_e32 v146, v32, v92
	v_fmac_f32_e32 v134, v45, v81
	v_fmac_f32_e32 v138, v41, v85
	v_fmac_f32_e32 v142, v37, v89
	v_fmac_f32_e32 v146, v33, v93
	v_fmac_f32_e32 v134, v46, v82
	v_fmac_f32_e32 v138, v42, v86
	v_fmac_f32_e32 v142, v38, v90
	v_fmac_f32_e32 v146, v34, v94
	v_fmac_f32_e32 v134, v47, v83
	v_fmac_f32_e32 v138, v43, v87
	v_fmac_f32_e32 v142, v39, v91
	v_fmac_f32_e32 v146, v35, v95
	v_max_f32_e32 v96, 0, v96
	v_max_f32_e32 v100, 0, v100
	v_max_f32_e32 v104, 0, v104
	v_max_f32_e32 v108, 0, v108
	v_max_f32_e32 v97, 0, v97
	v_max_f32_e32 v101, 0, v101
	v_max_f32_e32 v105, 0, v105
	v_max_f32_e32 v109, 0, v109
	v_max_f32_e32 v98, 0, v98
	v_max_f32_e32 v102, 0, v102
	v_max_f32_e32 v106, 0, v106
	v_max_f32_e32 v110, 0, v110
	v_max_f32_e32 v99, 0, v99
	v_max_f32_e32 v103, 0, v103
	v_max_f32_e32 v107, 0, v107
	v_max_f32_e32 v111, 0, v111
	v_mul_f32_e32 v135, v44, v96
	v_mul_f32_e32 v139, v40, v100
	v_mul_f32_e32 v143, v36, v104
	v_mul_f32_e32 v147, v32, v108
	v_fmac_f32_e32 v135, v45, v97
	v_fmac_f32_e32 v139, v41, v101
	v_fmac_f32_e32 v143, v37, v105
	v_fmac_f32_e32 v147, v33, v109
	v_fmac_f32_e32 v135, v46, v98
	v_fmac_f32_e32 v139, v42, v102
	v_fmac_f32_e32 v143, v38, v106
	v_fmac_f32_e32 v147, v34, v110
	v_fmac_f32_e32 v135, v47, v99
	v_fmac_f32_e32 v139, v43, v103
	v_fmac_f32_e32 v143, v39, v107
	v_fmac_f32_e32 v147, v35, v111
	s_nop 1
	v_permlane32_swap_b32_e32 v132, v134
	v_permlane32_swap_b32_e32 v133, v135
	v_permlane32_swap_b32_e32 v136, v138
	v_permlane32_swap_b32_e32 v137, v139
	v_permlane32_swap_b32_e32 v140, v142
	v_permlane32_swap_b32_e32 v141, v143
	v_permlane32_swap_b32_e32 v144, v146
	v_permlane32_swap_b32_e32 v145, v147
	v_add_f32_e32 v112, v132, v134
	v_add_f32_e32 v113, v133, v135
	v_add_f32_e32 v114, v136, v138
	v_add_f32_e32 v115, v137, v139
	v_add_f32_e32 v116, v140, v142
	v_add_f32_e32 v117, v141, v143
	v_add_f32_e32 v118, v144, v146
	v_add_f32_e32 v119, v145, v147
	s_nop 1
	v_permlane16_swap_b32_e32 v112, v113
	v_permlane16_swap_b32_e32 v114, v115
	v_permlane16_swap_b32_e32 v116, v117
	v_permlane16_swap_b32_e32 v118, v119
	v_add_u32_e32 v156, 0x800, v130
	v_add_u32_e32 v157, 0x800, v155
	v_add_f32_e32 v120, v112, v113
	v_add_f32_e32 v121, v114, v115
	v_add_f32_e32 v122, v116, v117
	v_add_f32_e32 v123, v118, v119
	v_ashrrev_i32_e32 v112, 31, v120
	v_ashrrev_i32_e32 v113, 31, v121
	v_ashrrev_i32_e32 v114, 31, v122
	v_ashrrev_i32_e32 v115, 31, v123
	v_cmp_le_u32_e32 vcc, v154, v124
	v_cmp_le_u32_e64 s[16:17], v154, v128
	v_cmp_le_u32_e64 s[44:45], v154, v129
	v_cmp_le_u32_e64 s[78:79], v154, v126
	v_or_b32_e32 v112, 0x80000000, v112
	v_or_b32_e32 v113, 0x80000000, v113
	v_or_b32_e32 v114, 0x80000000, v114
	v_or_b32_e32 v115, 0x80000000, v115
	v_xor_b32_e32 v120, v120, v112
	v_xor_b32_e32 v121, v121, v113
	v_xor_b32_e32 v122, v122, v114
	v_xor_b32_e32 v123, v123, v115
	v_cndmask_b32_e32 v120, 0, v120, vcc
	v_cndmask_b32_e64 v121, 0, v121, s[16:17]
	v_cndmask_b32_e64 v122, 0, v122, s[44:45]
	v_cndmask_b32_e64 v123, 0, v123, s[78:79]
	ds_write2st64_b32 v130, v120, v121 offset1:128
	ds_write2st64_b32 v155, v122, v123 offset1:128
	v_mov_b32_e32 v130, v156
	v_mov_b32_e32 v155, v157
	v_add_u32_e32 v154, 0x200, v154
	s_waitcnt vmcnt(0)
	s_branch .LBB0_479
	s_nop 0
	s_nop 0
	s_nop 0
	s_nop 0
	s_nop 0
	s_nop 0
	s_nop 0
	s_nop 0
	s_nop 0
	s_nop 0
	s_nop 0
	s_nop 0
